# mixer-B HB row loads with nt
# baseline (speedup 1.0000x reference)
.LBB0_314:
	s_or_b64 exec, exec, s[40:41]
	v_or_b32_e32 v187, s11, v233
	v_lshlrev_b32_e32 v187, 11, v187
	v_lshl_add_u32 v187, v210, 1, v187
	v_mov_b32_e32 v250, 0
	v_mov_b32_e32 v251, 0
	v_mov_b32_e32 v252, 0
	v_mov_b32_e32 v253, 0
	s_mov_b64 s[40:41], exec
	s_and_b64 exec, exec, s[8:9]
	v_add_u32_e32 v187, 0x38000, v187
	s_nop 0
	global_load_dwordx4 v[250:253], v187, s[50:51]
	v_add_u32_e32 v187, 0xfffc8000, v187
	s_mov_b64 exec, s[40:41]
	global_load_dwordx4 v[188:191], v187, s[50:51] nt
	v_add_u32_e32 v187, 0x8000, v187
	global_load_dwordx4 v[192:195], v187, s[50:51] nt
	v_add_u32_e32 v187, 0x8000, v187
	global_load_dwordx4 v[196:199], v187, s[50:51] nt
	v_add_u32_e32 v187, 0x8000, v187
	global_load_dwordx4 v[228:231], v187, s[50:51] nt
	v_add_u32_e32 v187, 0x28000, v187
	global_load_dwordx4 v[246:249], v187, s[50:51] nt
	v_mul_f32_e32 v144, 0xbfb8aa3b, v128
	v_mul_f32_e32 v145, 0xbfb8aa3b, v129
	v_exp_f32_e32 v144, v144
	v_exp_f32_e32 v145, v145
	v_mul_f32_e32 v146, 0xbfb8aa3b, v130
	v_mul_f32_e32 v147, 0xbfb8aa3b, v131
	v_exp_f32_e32 v146, v146
	v_exp_f32_e32 v147, v147
	v_add_f32_e32 v144, 1.0, v144
	v_add_f32_e32 v145, 1.0, v145
	v_rcp_f32_e32 v144, v144
	v_rcp_f32_e32 v145, v145
	v_add_f32_e32 v146, 1.0, v146
	v_add_f32_e32 v147, 1.0, v147
	v_rcp_f32_e32 v146, v146
	v_rcp_f32_e32 v147, v147
	v_pk_mul_f32 v[164:165], v[128:129], v[144:145]
	v_mul_f32_e32 v144, 0xbfb8aa3b, v120
	v_mul_f32_e32 v145, 0xbfb8aa3b, v121
	v_exp_f32_e32 v144, v144
	v_exp_f32_e32 v145, v145
	v_pk_mul_f32 v[166:167], v[130:131], v[146:147]
	v_mul_f32_e32 v146, 0xbfb8aa3b, v122
	v_mul_f32_e32 v147, 0xbfb8aa3b, v123
	v_exp_f32_e32 v146, v146
	v_exp_f32_e32 v147, v147
	v_add_f32_e32 v144, 1.0, v144
	v_add_f32_e32 v145, 1.0, v145
	v_rcp_f32_e32 v144, v144
	v_rcp_f32_e32 v145, v145
	v_or_b32_e32 v162, s11, v233
	v_add_f32_e32 v146, 1.0, v146
	v_add_f32_e32 v147, 1.0, v147
	v_rcp_f32_e32 v146, v146
	v_rcp_f32_e32 v147, v147
	v_ashrrev_i32_e32 v163, 31, v162
	v_pk_mul_f32 v[170:171], v[120:121], v[144:145]
	v_lshlrev_b64 v[144:145], 11, v[162:163]
	v_lshl_add_u64 v[144:145], s[50:51], 0, v[144:145]
	v_lshlrev_b64 v[160:161], 1, v[210:211]
	v_lshl_add_u64 v[144:145], v[144:145], 0, v[160:161]
	v_pk_mul_f32 v[168:169], v[122:123], v[146:147]
	s_waitcnt vmcnt(4)
	v_mov_b32_e32 v144, v188
	v_mov_b32_e32 v145, v189
	v_mov_b32_e32 v146, v190
	v_mov_b32_e32 v147, v191
	v_add_u32_e32 v187, 0x8000, v187
	global_load_dwordx4 v[188:191], v187, s[50:51] nt
	v_mov_b32_e32 v173, v211
	v_mov_b32_e32 v174, v211
	v_mov_b32_e32 v175, v211
	v_mov_b32_e32 v176, v211
	v_mov_b32_e32 v177, v211
	v_mov_b32_e32 v178, v211
	v_mov_b32_e32 v179, v211
	v_pk_mul_f32 v[170:171], v[124:125], v[170:171]
	v_pk_mul_f32 v[168:169], v[126:127], v[168:169]
	v_mov_b32_e32 v184, v211
	v_mov_b32_e32 v185, v211
	s_movk_i32 s16, 0x7ff
	v_cndmask_b32_e64 v172, v144, v156, s[4:5]
	v_cndmask_b32_e64 v156, v156, v144, s[0:1]
	s_nop 0
	v_mov_b32_dpp v173, v172 row_ror:1 row_mask:0xf bank_mask:0xf
	v_mov_b32_e32 v172, v211
	s_nop 1
	v_mov_b32_dpp v172, v156 row_ror:2 row_mask:0xf bank_mask:0xf
	v_cndmask_b32_e64 v156, v145, v157, s[4:5]
	v_cndmask_b32_e64 v157, v157, v145, s[0:1]
	v_lshlrev_b32_e32 v180, 16, v172
	v_mov_b32_dpp v174, v156 row_ror:1 row_mask:0xf bank_mask:0xf
	v_mov_b32_dpp v175, v157 row_ror:2 row_mask:0xf bank_mask:0xf
	v_cndmask_b32_e64 v156, v146, v158, s[4:5]
	v_cndmask_b32_e64 v157, v158, v146, s[0:1]
	v_lshlrev_b32_e32 v158, 16, v144
	v_mov_b32_dpp v176, v156 row_ror:1 row_mask:0xf bank_mask:0xf
	v_mov_b32_dpp v177, v157 row_ror:2 row_mask:0xf bank_mask:0xf
	v_cndmask_b32_e64 v156, v147, v159, s[4:5]
	v_cndmask_b32_e64 v157, v159, v147, s[0:1]
	v_lshlrev_b32_e32 v159, 16, v173
	v_mov_b32_dpp v178, v156 row_ror:1 row_mask:0xf bank_mask:0xf
	v_mov_b32_dpp v179, v157 row_ror:2 row_mask:0xf bank_mask:0xf
	v_mov_b32_e32 v156, v152
	v_mov_b32_e32 v157, v140
	v_pk_mul_f32 v[158:159], v[156:157], v[158:159]
	v_and_b32_e32 v172, 0xffff0000, v172
	v_fma_f32 v140, v136, v180, v159
	v_add_f32_e32 v180, v158, v140
	v_and_b32_e32 v159, 0xffff0000, v173
	v_and_b32_e32 v158, 0xffff0000, v144
	v_mov_b32_e32 v140, v153
	v_pk_mul_f32 v[152:153], v[140:141], v[158:159]
	v_lshlrev_b32_e32 v158, 16, v145
	v_fma_f32 v153, v137, v172, v153
	v_add_f32_e32 v172, v152, v153
	v_lshlrev_b32_e32 v159, 16, v174
	v_mov_b32_e32 v152, v154
	v_mov_b32_e32 v153, v142
	v_lshlrev_b32_e32 v173, 16, v175
	v_pk_mul_f32 v[158:159], v[152:153], v[158:159]
	v_and_b32_e32 v175, 0xffff0000, v175
	v_fma_f32 v142, v138, v173, v159
	v_add_f32_e32 v173, v158, v142
	v_and_b32_e32 v159, 0xffff0000, v174
	v_and_b32_e32 v158, 0xffff0000, v145
	v_mov_b32_e32 v142, v155
	v_pk_mul_f32 v[154:155], v[142:143], v[158:159]
	v_lshlrev_b32_e32 v158, 16, v146
	v_fma_f32 v155, v139, v175, v155
	v_add_f32_e32 v174, v154, v155
	v_lshlrev_b32_e32 v159, 16, v176
	v_mov_b32_e32 v154, v148
	v_mov_b32_e32 v155, v116
	v_lshlrev_b32_e32 v175, 16, v177
	v_pk_mul_f32 v[158:159], v[154:155], v[158:159]
	v_and_b32_e32 v177, 0xffff0000, v177
	v_fma_f32 v116, v112, v175, v159
	v_add_f32_e32 v175, v158, v116
	v_and_b32_e32 v159, 0xffff0000, v176
	v_and_b32_e32 v158, 0xffff0000, v146
	v_mov_b32_e32 v116, v149
	v_pk_mul_f32 v[148:149], v[116:117], v[158:159]
	v_mov_b32_e32 v158, v150
	v_fma_f32 v149, v113, v177, v149
	v_add_f32_e32 v176, v148, v149
	v_lshlrev_b32_e32 v148, 16, v147
	v_lshlrev_b32_e32 v149, 16, v178
	v_mov_b32_e32 v159, v118
	v_lshlrev_b32_e32 v177, 16, v179
	v_pk_mul_f32 v[148:149], v[158:159], v[148:149]
	v_and_b32_e32 v150, 0xffff0000, v179
	v_fma_f32 v118, v114, v177, v149
	v_add_f32_e32 v177, v148, v118
	v_and_b32_e32 v149, 0xffff0000, v178
	v_and_b32_e32 v148, 0xffff0000, v147
	v_mov_b32_e32 v118, v151
	v_pk_mul_f32 v[148:149], v[118:119], v[148:149]
	v_mov_b32_e32 v179, v211
	v_fma_f32 v149, v115, v150, v149
	v_add_f32_e32 v178, v148, v149
	v_pk_mul_f32 v[148:149], v[132:133], v[164:165]
	v_pk_mul_f32 v[150:151], v[134:135], v[166:167]
	v_mul_f32_e32 v148, v148, v180
	v_mul_f32_e32 v149, v149, v172
	v_cvt_pk_bf16_f32 v148, v148, v149
	v_mul_f32_e32 v149, v150, v173
	v_mul_f32_e32 v150, v151, v174
	v_cvt_pk_bf16_f32 v149, v149, v150
	v_mul_f32_e32 v150, v170, v175
	v_mul_f32_e32 v151, v171, v176
	v_cvt_pk_bf16_f32 v150, v150, v151
	v_mul_f32_e32 v151, v168, v177
	v_mul_f32_e32 v164, v169, v178
	v_cvt_pk_bf16_f32 v151, v151, v164
	v_lshlrev_b64 v[164:165], 12, v[162:163]
	v_lshl_add_u64 v[164:165], s[12:13], 0, v[164:165]
	v_lshl_add_u64 v[164:165], v[164:165], 0, v[160:161]
	global_store_dwordx4 v[164:165], v[148:151], off offset:2048
	v_or_b32_e32 v172, 16, v162
	v_ashrrev_i32_e32 v173, 31, v172
	v_mul_f32_e32 v148, 0xbfb8aa3b, v104
	v_mul_f32_e32 v149, 0xbfb8aa3b, v105
	v_exp_f32_e32 v148, v148
	v_exp_f32_e32 v149, v149
	v_mul_f32_e32 v150, 0xbfb8aa3b, v106
	v_mul_f32_e32 v151, 0xbfb8aa3b, v107
	v_exp_f32_e32 v150, v150
	v_exp_f32_e32 v151, v151
	v_add_f32_e32 v148, 1.0, v148
	v_add_f32_e32 v149, 1.0, v149
	v_rcp_f32_e32 v148, v148
	v_rcp_f32_e32 v149, v149
	v_add_f32_e32 v150, 1.0, v150
	v_add_f32_e32 v151, 1.0, v151
	v_rcp_f32_e32 v150, v150
	v_rcp_f32_e32 v151, v151
	v_pk_mul_f32 v[164:165], v[104:105], v[148:149]
	v_mul_f32_e32 v148, 0xbfb8aa3b, v96
	v_mul_f32_e32 v149, 0xbfb8aa3b, v97
	v_exp_f32_e32 v148, v148
	v_exp_f32_e32 v149, v149
	v_pk_mul_f32 v[166:167], v[106:107], v[150:151]
	v_mul_f32_e32 v150, 0xbfb8aa3b, v98
	v_mul_f32_e32 v151, 0xbfb8aa3b, v99
	v_exp_f32_e32 v150, v150
	v_exp_f32_e32 v151, v151
	v_add_f32_e32 v148, 1.0, v148
	v_add_f32_e32 v149, 1.0, v149
	v_rcp_f32_e32 v148, v148
	v_rcp_f32_e32 v149, v149
	v_add_f32_e32 v150, 1.0, v150
	v_add_f32_e32 v151, 1.0, v151
	v_rcp_f32_e32 v150, v150
	v_rcp_f32_e32 v151, v151
	v_pk_mul_f32 v[168:169], v[96:97], v[148:149]
	v_lshlrev_b64 v[148:149], 11, v[172:173]
	v_lshl_add_u64 v[148:149], s[50:51], 0, v[148:149]
	v_lshl_add_u64 v[148:149], v[148:149], 0, v[160:161]
	v_pk_mul_f32 v[170:171], v[98:99], v[150:151]
	s_waitcnt vmcnt(5)
	v_mov_b32_e32 v148, v192
	v_mov_b32_e32 v149, v193
	v_mov_b32_e32 v150, v194
	v_mov_b32_e32 v151, v195
	v_add_u32_e32 v187, 0x8000, v187
	global_load_dwordx4 v[192:195], v187, s[50:51] nt
	v_mov_b32_e32 v174, v211
	v_mov_b32_e32 v175, v211
	v_mov_b32_e32 v176, v211
	v_mov_b32_e32 v177, v211
	v_mov_b32_e32 v178, v211
	v_mov_b32_e32 v180, v211
	v_pk_mul_f32 v[166:167], v[110:111], v[166:167]
	v_pk_mul_f32 v[170:171], v[102:103], v[170:171]
	v_cndmask_b32_e64 v163, v148, v144, s[4:5]
	v_cndmask_b32_e64 v144, v144, v148, s[0:1]
	s_nop 0
	v_mov_b32_dpp v174, v163 row_ror:1 row_mask:0xf bank_mask:0xf
	v_mov_b32_e32 v163, v211
	s_nop 1
	v_mov_b32_dpp v163, v144 row_ror:2 row_mask:0xf bank_mask:0xf
	v_cndmask_b32_e64 v144, v149, v145, s[4:5]
	v_cndmask_b32_e64 v145, v145, v149, s[0:1]
	s_nop 0
	v_mov_b32_dpp v175, v144 row_ror:1 row_mask:0xf bank_mask:0xf
	v_mov_b32_dpp v176, v145 row_ror:2 row_mask:0xf bank_mask:0xf
	v_cndmask_b32_e64 v144, v150, v146, s[4:5]
	v_cndmask_b32_e64 v145, v146, v150, s[0:1]
	s_nop 0
	v_mov_b32_dpp v177, v144 row_ror:1 row_mask:0xf bank_mask:0xf
	v_mov_b32_dpp v178, v145 row_ror:2 row_mask:0xf bank_mask:0xf
	v_cndmask_b32_e64 v144, v151, v147, s[4:5]
	v_cndmask_b32_e64 v145, v147, v151, s[0:1]
	v_pk_mul_f32 v[146:147], v[100:101], v[168:169]
	v_mov_b32_dpp v179, v144 row_ror:1 row_mask:0xf bank_mask:0xf
	v_mov_b32_dpp v180, v145 row_ror:2 row_mask:0xf bank_mask:0xf
	v_lshlrev_b32_e32 v145, 16, v174
	v_lshlrev_b32_e32 v144, 16, v148
	v_lshlrev_b32_e32 v168, 16, v163
	v_pk_mul_f32 v[144:145], v[156:157], v[144:145]
	v_and_b32_e32 v163, 0xffff0000, v163
	v_fma_f32 v145, v136, v168, v145
	v_add_f32_e32 v168, v144, v145
	v_and_b32_e32 v145, 0xffff0000, v174
	v_and_b32_e32 v144, 0xffff0000, v148
	v_pk_mul_f32 v[144:145], v[140:141], v[144:145]
	v_lshlrev_b32_e32 v169, 16, v176
	v_fma_f32 v145, v137, v163, v145
	v_add_f32_e32 v163, v144, v145
	v_lshlrev_b32_e32 v145, 16, v175
	v_lshlrev_b32_e32 v144, 16, v149
	v_pk_mul_f32 v[144:145], v[152:153], v[144:145]
	v_and_b32_e32 v174, 0xffff0000, v176
	v_fma_f32 v145, v138, v169, v145
	v_add_f32_e32 v169, v144, v145
	v_and_b32_e32 v145, 0xffff0000, v175
	v_and_b32_e32 v144, 0xffff0000, v149
	v_pk_mul_f32 v[144:145], v[142:143], v[144:145]
	v_lshlrev_b32_e32 v175, 16, v178
	v_fma_f32 v145, v139, v174, v145
	v_add_f32_e32 v174, v144, v145
	v_lshlrev_b32_e32 v145, 16, v177
	v_lshlrev_b32_e32 v144, 16, v150
	v_pk_mul_f32 v[144:145], v[154:155], v[144:145]
	v_and_b32_e32 v176, 0xffff0000, v178
	v_fma_f32 v145, v112, v175, v145
	v_add_f32_e32 v175, v144, v145
	v_and_b32_e32 v145, 0xffff0000, v177
	v_and_b32_e32 v144, 0xffff0000, v150
	v_pk_mul_f32 v[144:145], v[116:117], v[144:145]
	v_lshlrev_b32_e32 v177, 16, v180
	v_fma_f32 v145, v113, v176, v145
	v_add_f32_e32 v176, v144, v145
	v_lshlrev_b32_e32 v145, 16, v179
	v_lshlrev_b32_e32 v144, 16, v151
	v_pk_mul_f32 v[144:145], v[158:159], v[144:145]
	v_and_b32_e32 v178, 0xffff0000, v180
	v_fma_f32 v145, v114, v177, v145
	v_add_f32_e32 v177, v144, v145
	v_and_b32_e32 v145, 0xffff0000, v179
	v_and_b32_e32 v144, 0xffff0000, v151
	v_pk_mul_f32 v[144:145], v[118:119], v[144:145]
	v_mul_f32_e32 v146, v146, v175
	v_fma_f32 v145, v115, v178, v145
	v_add_f32_e32 v178, v144, v145
	v_pk_mul_f32 v[144:145], v[108:109], v[164:165]
	v_lshlrev_b64 v[164:165], 12, v[172:173]
	v_mul_f32_e32 v144, v144, v168
	v_mul_f32_e32 v145, v145, v163
	v_cvt_pk_bf16_f32 v144, v144, v145
	v_mul_f32_e32 v145, v166, v169
	v_mul_f32_e32 v147, v147, v176
	v_lshl_add_u64 v[164:165], s[12:13], 0, v[164:165]
	v_mul_f32_e32 v163, v167, v174
	v_cvt_pk_bf16_f32 v145, v145, v163
	v_cvt_pk_bf16_f32 v146, v146, v147
	v_mul_f32_e32 v147, v170, v177
	v_lshl_add_u64 v[164:165], v[164:165], 0, v[160:161]
	v_mul_f32_e32 v163, v171, v178
	v_cvt_pk_bf16_f32 v147, v147, v163
	global_store_dwordx4 v[164:165], v[144:147], off offset:2048
	v_or_b32_e32 v172, 32, v162
	v_ashrrev_i32_e32 v173, 31, v172
	v_mul_f32_e32 v144, 0xbfb8aa3b, v88
	v_mul_f32_e32 v145, 0xbfb8aa3b, v89
	v_exp_f32_e32 v144, v144
	v_exp_f32_e32 v145, v145
	v_mul_f32_e32 v146, 0xbfb8aa3b, v90
	v_mul_f32_e32 v147, 0xbfb8aa3b, v91
	v_exp_f32_e32 v146, v146
	v_exp_f32_e32 v147, v147
	v_add_f32_e32 v144, 1.0, v144
	v_add_f32_e32 v145, 1.0, v145
	v_rcp_f32_e32 v144, v144
	v_rcp_f32_e32 v145, v145
	v_add_f32_e32 v146, 1.0, v146
	v_add_f32_e32 v147, 1.0, v147
	v_rcp_f32_e32 v146, v146
	v_rcp_f32_e32 v147, v147
	v_pk_mul_f32 v[164:165], v[88:89], v[144:145]
	v_mul_f32_e32 v144, 0xbfb8aa3b, v80
	v_mul_f32_e32 v145, 0xbfb8aa3b, v81
	v_exp_f32_e32 v144, v144
	v_exp_f32_e32 v145, v145
	v_pk_mul_f32 v[166:167], v[90:91], v[146:147]
	v_mul_f32_e32 v146, 0xbfb8aa3b, v82
	v_mul_f32_e32 v147, 0xbfb8aa3b, v83
	v_exp_f32_e32 v146, v146
	v_exp_f32_e32 v147, v147
	v_add_f32_e32 v144, 1.0, v144
	v_add_f32_e32 v145, 1.0, v145
	v_rcp_f32_e32 v144, v144
	v_rcp_f32_e32 v145, v145
	v_add_f32_e32 v146, 1.0, v146
	v_add_f32_e32 v147, 1.0, v147
	v_rcp_f32_e32 v146, v146
	v_rcp_f32_e32 v147, v147
	v_pk_mul_f32 v[168:169], v[80:81], v[144:145]
	v_lshlrev_b64 v[144:145], 11, v[172:173]
	v_lshl_add_u64 v[144:145], s[50:51], 0, v[144:145]
	v_lshl_add_u64 v[144:145], v[144:145], 0, v[160:161]
	v_pk_mul_f32 v[170:171], v[82:83], v[146:147]
	s_waitcnt vmcnt(6)
	v_mov_b32_e32 v144, v196
	v_mov_b32_e32 v145, v197
	v_mov_b32_e32 v146, v198
	v_mov_b32_e32 v147, v199
	v_add_u32_e32 v187, 0x8000, v187
	global_load_dwordx4 v[196:199], v187, s[50:51] nt
	v_mov_b32_e32 v174, v211
	v_mov_b32_e32 v175, v211
	v_mov_b32_e32 v176, v211
	v_mov_b32_e32 v177, v211
	v_mov_b32_e32 v178, v211
	v_mov_b32_e32 v179, v211
	v_mov_b32_e32 v180, v211
	v_pk_mul_f32 v[166:167], v[94:95], v[166:167]
	v_pk_mul_f32 v[170:171], v[86:87], v[170:171]
	v_cndmask_b32_e64 v163, v144, v148, s[4:5]
	v_cndmask_b32_e64 v148, v148, v144, s[0:1]
	s_nop 0
	v_mov_b32_dpp v174, v163 row_ror:1 row_mask:0xf bank_mask:0xf
	v_mov_b32_e32 v163, v211
	s_nop 1
	v_mov_b32_dpp v163, v148 row_ror:2 row_mask:0xf bank_mask:0xf
	v_cndmask_b32_e64 v148, v145, v149, s[4:5]
	v_cndmask_b32_e64 v149, v149, v145, s[0:1]
	s_nop 0
	v_mov_b32_dpp v175, v148 row_ror:1 row_mask:0xf bank_mask:0xf
	v_mov_b32_dpp v176, v149 row_ror:2 row_mask:0xf bank_mask:0xf
	v_cndmask_b32_e64 v148, v146, v150, s[4:5]
	v_cndmask_b32_e64 v149, v150, v146, s[0:1]
	s_nop 0
	v_mov_b32_dpp v177, v148 row_ror:1 row_mask:0xf bank_mask:0xf
	v_mov_b32_dpp v178, v149 row_ror:2 row_mask:0xf bank_mask:0xf
	v_cndmask_b32_e64 v148, v147, v151, s[4:5]
	v_cndmask_b32_e64 v149, v151, v147, s[0:1]
	v_pk_mul_f32 v[150:151], v[84:85], v[168:169]
	v_mov_b32_dpp v179, v148 row_ror:1 row_mask:0xf bank_mask:0xf
	v_mov_b32_dpp v180, v149 row_ror:2 row_mask:0xf bank_mask:0xf
	v_lshlrev_b32_e32 v149, 16, v174
	v_lshlrev_b32_e32 v148, 16, v144
	v_lshlrev_b32_e32 v168, 16, v163
	v_pk_mul_f32 v[148:149], v[156:157], v[148:149]
	v_and_b32_e32 v163, 0xffff0000, v163
	v_fma_f32 v149, v136, v168, v149
	v_add_f32_e32 v168, v148, v149
	v_and_b32_e32 v149, 0xffff0000, v174
	v_and_b32_e32 v148, 0xffff0000, v144
	v_pk_mul_f32 v[148:149], v[140:141], v[148:149]
	v_lshlrev_b32_e32 v169, 16, v176
	v_fma_f32 v149, v137, v163, v149
	v_add_f32_e32 v163, v148, v149
	v_lshlrev_b32_e32 v149, 16, v175
	v_lshlrev_b32_e32 v148, 16, v145
	v_pk_mul_f32 v[148:149], v[152:153], v[148:149]
	v_and_b32_e32 v174, 0xffff0000, v176
	v_fma_f32 v149, v138, v169, v149
	v_add_f32_e32 v169, v148, v149
	v_and_b32_e32 v149, 0xffff0000, v175
	v_and_b32_e32 v148, 0xffff0000, v145
	v_pk_mul_f32 v[148:149], v[142:143], v[148:149]
	v_lshlrev_b32_e32 v175, 16, v178
	v_fma_f32 v149, v139, v174, v149
	v_add_f32_e32 v174, v148, v149
	v_lshlrev_b32_e32 v149, 16, v177
	v_lshlrev_b32_e32 v148, 16, v146
	v_pk_mul_f32 v[148:149], v[154:155], v[148:149]
	v_and_b32_e32 v176, 0xffff0000, v178
	v_fma_f32 v149, v112, v175, v149
	v_add_f32_e32 v175, v148, v149
	v_and_b32_e32 v149, 0xffff0000, v177
	v_and_b32_e32 v148, 0xffff0000, v146
	v_pk_mul_f32 v[148:149], v[116:117], v[148:149]
	v_lshlrev_b32_e32 v177, 16, v180
	v_fma_f32 v149, v113, v176, v149
	v_add_f32_e32 v176, v148, v149
	v_lshlrev_b32_e32 v149, 16, v179
	v_lshlrev_b32_e32 v148, 16, v147
	v_pk_mul_f32 v[148:149], v[158:159], v[148:149]
	v_and_b32_e32 v178, 0xffff0000, v180
	v_fma_f32 v149, v114, v177, v149
	v_add_f32_e32 v177, v148, v149
	v_and_b32_e32 v149, 0xffff0000, v179
	v_and_b32_e32 v148, 0xffff0000, v147
	v_pk_mul_f32 v[148:149], v[118:119], v[148:149]
	v_mul_f32_e32 v150, v150, v175
	v_fma_f32 v149, v115, v178, v149
	v_add_f32_e32 v178, v148, v149
	v_pk_mul_f32 v[148:149], v[92:93], v[164:165]
	v_mul_f32_e32 v151, v151, v176
	v_mul_f32_e32 v148, v148, v168
	v_mul_f32_e32 v149, v149, v163
	v_or_b32_e32 v168, 48, v162
	v_cvt_pk_bf16_f32 v148, v148, v149
	v_mul_f32_e32 v149, v166, v169
	v_mul_f32_e32 v163, v167, v174
	v_lshlrev_b64 v[164:165], 12, v[172:173]
	v_ashrrev_i32_e32 v169, 31, v168
	v_cvt_pk_bf16_f32 v149, v149, v163
	v_cvt_pk_bf16_f32 v150, v150, v151
	v_mul_f32_e32 v151, v170, v177
	v_mul_f32_e32 v163, v171, v178
	v_lshl_add_u64 v[164:165], s[12:13], 0, v[164:165]
	v_lshlrev_b64 v[170:171], 11, v[168:169]
	v_lshl_add_u64 v[164:165], v[164:165], 0, v[160:161]
	v_lshl_add_u64 v[170:171], s[50:51], 0, v[170:171]
	v_cvt_pk_bf16_f32 v151, v151, v163
	global_store_dwordx4 v[164:165], v[148:151], off offset:2048
	v_lshl_add_u64 v[170:171], v[170:171], 0, v[160:161]
	s_waitcnt vmcnt(7)
	v_mov_b32_e32 v176, v228
	v_mov_b32_e32 v177, v229
	v_mov_b32_e32 v178, v230
	v_mov_b32_e32 v179, v231
	v_mul_f32_e32 v148, 0xbfb8aa3b, v72
	v_mul_f32_e32 v149, 0xbfb8aa3b, v73
	v_exp_f32_e32 v148, v148
	v_exp_f32_e32 v149, v149
	v_mul_f32_e32 v150, 0xbfb8aa3b, v74
	v_mul_f32_e32 v151, 0xbfb8aa3b, v75
	v_add_f32_e32 v148, 1.0, v148
	v_add_f32_e32 v149, 1.0, v149
	v_rcp_f32_e32 v148, v148
	v_rcp_f32_e32 v149, v149
	v_exp_f32_e32 v150, v150
	v_exp_f32_e32 v151, v151
	v_mov_b32_e32 v170, v211
	v_pk_mul_f32 v[164:165], v[72:73], v[148:149]
	v_mul_f32_e32 v148, 0xbfb8aa3b, v64
	v_mul_f32_e32 v149, 0xbfb8aa3b, v65
	v_exp_f32_e32 v148, v148
	v_exp_f32_e32 v149, v149
	v_add_f32_e32 v150, 1.0, v150
	v_add_f32_e32 v151, 1.0, v151
	v_add_f32_e32 v148, 1.0, v148
	v_add_f32_e32 v149, 1.0, v149
	v_rcp_f32_e32 v148, v148
	v_rcp_f32_e32 v149, v149
	v_rcp_f32_e32 v150, v150
	v_rcp_f32_e32 v151, v151
	v_mov_b32_e32 v172, v211
	v_mov_b32_e32 v173, v211
	v_mov_b32_e32 v174, v211
	v_mov_b32_e32 v175, v211
	v_pk_mul_f32 v[148:149], v[64:65], v[148:149]
	v_pk_mul_f32 v[166:167], v[74:75], v[150:151]
	v_mul_f32_e32 v150, 0xbfb8aa3b, v66
	v_mul_f32_e32 v151, 0xbfb8aa3b, v67
	v_pk_mul_f32 v[182:183], v[68:69], v[148:149]
	v_exp_f32_e32 v150, v150
	v_exp_f32_e32 v151, v151
	v_pk_mul_f32 v[164:165], v[76:77], v[164:165]
	v_pk_mul_f32 v[166:167], v[78:79], v[166:167]
	v_add_f32_e32 v150, 1.0, v150
	v_add_f32_e32 v151, 1.0, v151
	v_rcp_f32_e32 v150, v150
	v_rcp_f32_e32 v151, v151
	v_cndmask_b32_e64 v163, v176, v144, s[4:5]
	v_cndmask_b32_e64 v144, v144, v176, s[0:1]
	s_nop 0
	v_mov_b32_dpp v170, v163 row_ror:1 row_mask:0xf bank_mask:0xf
	v_mov_b32_e32 v163, v211
	v_and_b32_e32 v171, 0xffff0000, v170
	v_pk_mul_f32 v[150:151], v[66:67], v[150:151]
	v_mov_b32_dpp v163, v144 row_ror:2 row_mask:0xf bank_mask:0xf
	v_cndmask_b32_e64 v144, v177, v145, s[4:5]
	v_cndmask_b32_e64 v145, v145, v177, s[0:1]
	v_lshlrev_b32_e32 v148, 16, v163
	v_mov_b32_dpp v172, v144 row_ror:1 row_mask:0xf bank_mask:0xf
	v_mov_b32_dpp v173, v145 row_ror:2 row_mask:0xf bank_mask:0xf
	v_cndmask_b32_e64 v144, v178, v146, s[4:5]
	v_cndmask_b32_e64 v145, v146, v178, s[0:1]
	v_pk_mul_f32 v[180:181], v[70:71], v[150:151]
	v_mov_b32_dpp v174, v144 row_ror:1 row_mask:0xf bank_mask:0xf
	v_mov_b32_dpp v175, v145 row_ror:2 row_mask:0xf bank_mask:0xf
	v_cndmask_b32_e64 v144, v179, v147, s[4:5]
	v_cndmask_b32_e64 v145, v147, v179, s[0:1]
	s_nop 0
	v_mov_b32_dpp v184, v144 row_ror:1 row_mask:0xf bank_mask:0xf
	v_mov_b32_dpp v185, v145 row_ror:2 row_mask:0xf bank_mask:0xf
	v_lshlrev_b32_e32 v145, 16, v170
	v_lshlrev_b32_e32 v144, 16, v176
	v_pk_mul_f32 v[146:147], v[156:157], v[144:145]
	v_and_b32_e32 v170, 0xffff0000, v176
	v_fma_f32 v145, v136, v148, v147
	v_add_f32_e32 v186, v146, v145
	v_and_b32_e32 v145, 0xffff0000, v163
	v_pk_mul_f32 v[146:147], v[140:141], v[170:171]
	s_nop 0
	v_fma_f32 v145, v137, v145, v147
	v_add_f32_e32 v163, v146, v145
	v_lshlrev_b32_e32 v147, 16, v172
	v_lshlrev_b32_e32 v146, 16, v177
	v_lshlrev_b32_e32 v145, 16, v173
	v_pk_mul_f32 v[148:149], v[152:153], v[146:147]
	v_mul_f32_e32 v163, v165, v163
	v_fma_f32 v145, v138, v145, v149
	v_add_f32_e32 v147, v148, v145
	v_and_b32_e32 v145, 0xffff0000, v173
	v_and_b32_e32 v173, 0xffff0000, v172
	v_and_b32_e32 v172, 0xffff0000, v177
	v_pk_mul_f32 v[148:149], v[142:143], v[172:173]
	v_mul_f32_e32 v147, v166, v147
	v_fma_f32 v145, v139, v145, v149
	v_add_f32_e32 v171, v148, v145
	v_lshlrev_b32_e32 v149, 16, v174
	v_lshlrev_b32_e32 v148, 16, v178
	v_lshlrev_b32_e32 v145, 16, v175
	v_pk_mul_f32 v[150:151], v[154:155], v[148:149]
	s_nop 0
	v_fma_f32 v145, v112, v145, v151
	v_add_f32_e32 v149, v150, v145
	v_and_b32_e32 v145, 0xffff0000, v175
	v_and_b32_e32 v175, 0xffff0000, v174
	v_and_b32_e32 v174, 0xffff0000, v178
	v_pk_mul_f32 v[150:151], v[116:117], v[174:175]
	s_nop 0
	v_fma_f32 v145, v113, v145, v151
	v_add_f32_e32 v173, v150, v145
	v_lshlrev_b32_e32 v151, 16, v184
	v_lshlrev_b32_e32 v150, 16, v179
	v_lshlrev_b32_e32 v145, 16, v185
	v_pk_mul_f32 v[176:177], v[158:159], v[150:151]
	s_nop 0
	v_fma_f32 v145, v114, v145, v177
	v_add_f32_e32 v151, v176, v145
	v_and_b32_e32 v177, 0xffff0000, v184
	v_and_b32_e32 v176, 0xffff0000, v179
	v_and_b32_e32 v145, 0xffff0000, v185
	v_pk_mul_f32 v[178:179], v[118:119], v[176:177]
	s_nop 0
	v_fma_f32 v145, v115, v145, v179
	v_add_f32_e32 v175, v178, v145
	v_bitop3_b32 v145, v162, s16, 48 bitop3:0xc8
	v_mul_f32_e32 v162, v164, v186
	v_cvt_pk_bf16_f32 v162, v162, v163
	v_mul_f32_e32 v163, v167, v171
	v_lshlrev_b64 v[166:167], 12, v[168:169]
	v_lshl_add_u64 v[166:167], s[12:13], 0, v[166:167]
	s_movk_i32 s16, 0x7fd
	v_cvt_pk_bf16_f32 v163, v147, v163
	v_mul_f32_e32 v147, v182, v149
	v_mul_f32_e32 v149, v183, v173
	v_lshl_add_u64 v[166:167], v[166:167], 0, v[160:161]
	v_cmp_lt_u32_e32 vcc, s16, v145
	v_cvt_pk_bf16_f32 v164, v147, v149
	v_mul_f32_e32 v147, v180, v151
	v_mul_f32_e32 v149, v181, v175
	v_cvt_pk_bf16_f32 v165, v147, v149
	global_store_dwordx4 v[166:167], v[162:165], off offset:2048
	s_and_saveexec_b64 s[40:41], vcc
	s_cbranch_execz .LBB0_316
	v_lshrrev_b32_e32 v147, 21, v169
	v_add_u32_e32 v147, v168, v147
	v_ashrrev_i32_e32 v162, 11, v147
	v_ashrrev_i32_e32 v163, 31, v162
	v_add_u32_e32 v164, 0xfffff802, v145
	v_mov_b32_e32 v165, v211
	v_lshlrev_b64 v[162:163], 13, v[162:163]
	v_lshl_add_u64 v[162:163], s[18:19], 0, v[162:163]
	v_lshlrev_b64 v[164:165], 12, v[164:165]
	v_lshl_add_u64 v[162:163], v[162:163], 0, v[164:165]
	v_lshl_add_u64 v[162:163], v[210:211], 2, v[162:163]
	v_mov_b32_e32 v145, v170
	v_mov_b32_e32 v147, v172
	v_mov_b32_e32 v149, v174
	v_mov_b32_e32 v151, v176
	global_store_dwordx4 v[162:163], v[144:147], off
	global_store_dwordx4 v[162:163], v[148:151], off offset:16
